# attention: PV MFMAs of the first query sub-tile start earlier in the second sub-tile's softmax stream (spacing 9, first at op 8)
# baseline (speedup 1.0000x reference)
.Lat_nr1:
	v_exp_f32_e32 v64, v64
	v_exp_f32_e32 v65, v65
	v_exp_f32_e32 v66, v66
	v_exp_f32_e32 v67, v67
	v_add_f32_e32 v202, v202, v64
	v_exp_f32_e32 v68, v68
	v_exp_f32_e32 v69, v69
	v_add_f32_e32 v202, v202, v66
	v_exp_f32_e32 v70, v70
	v_add_f32_e32 v214, v65, v67
	v_cvt_pk_bf16_f32 v64, v64, v65
	v_exp_f32_e32 v71, v71
	v_add_f32_e32 v202, v202, v68
	v_exp_f32_e32 v72, v72
	v_add_f32_e32 v214, v214, v69
	v_cvt_pk_bf16_f32 v65, v66, v67
	v_exp_f32_e32 v73, v73
	v_add_f32_e32 v202, v202, v70
	v_exp_f32_e32 v74, v74
	v_add_f32_e32 v214, v214, v71
	v_cvt_pk_bf16_f32 v66, v68, v69
	v_exp_f32_e32 v75, v75
	v_add_f32_e32 v202, v202, v72
	v_exp_f32_e32 v76, v76
	v_add_f32_e32 v214, v214, v73
	v_cvt_pk_bf16_f32 v67, v70, v71
	v_exp_f32_e32 v77, v77
	v_add_f32_e32 v202, v202, v74
	s_waitcnt lgkmcnt(3)
	v_mfma_f32_32x32x16_bf16 v[16:31], v[236:239], v[64:67], v[16:31]
	v_exp_f32_e32 v78, v78
	v_add_f32_e32 v214, v214, v75
	v_cvt_pk_bf16_f32 v68, v72, v73
	v_exp_f32_e32 v79, v79
	v_add_f32_e32 v202, v202, v76
	v_exp_f32_e32 v80, v80
	v_add_f32_e32 v214, v214, v77
	v_cvt_pk_bf16_f32 v69, v74, v75
	v_exp_f32_e32 v81, v81
	s_waitcnt lgkmcnt(2)
	v_mfma_f32_32x32x16_bf16 v[0:15], v[240:243], v[64:67], v[0:15]
	v_add_f32_e32 v202, v202, v78
	v_exp_f32_e32 v82, v82
	v_add_f32_e32 v214, v214, v79
	v_cvt_pk_bf16_f32 v70, v76, v77
	v_exp_f32_e32 v83, v83
	v_add_f32_e32 v202, v202, v80
	v_exp_f32_e32 v84, v84
	v_add_f32_e32 v214, v214, v81
	v_cvt_pk_bf16_f32 v71, v78, v79
	v_exp_f32_e32 v85, v85
	v_add_f32_e32 v202, v202, v82
	s_waitcnt lgkmcnt(1)
	v_mfma_f32_32x32x16_bf16 v[16:31], v[244:247], v[68:71], v[16:31]
	v_exp_f32_e32 v86, v86
	v_add_f32_e32 v214, v214, v83
	v_cvt_pk_bf16_f32 v72, v80, v81
	v_exp_f32_e32 v87, v87
	v_add_f32_e32 v202, v202, v84
	v_exp_f32_e32 v88, v88
	v_add_f32_e32 v214, v214, v85
	v_cvt_pk_bf16_f32 v73, v82, v83
	v_exp_f32_e32 v89, v89
	s_waitcnt lgkmcnt(0)
	v_mfma_f32_32x32x16_bf16 v[0:15], v[248:251], v[68:71], v[0:15]
	v_add_f32_e32 v202, v202, v86
	v_exp_f32_e32 v90, v90
	v_add_f32_e32 v214, v214, v87
	v_cvt_pk_bf16_f32 v74, v84, v85
	v_exp_f32_e32 v91, v91
	v_add_f32_e32 v202, v202, v88
	v_exp_f32_e32 v92, v92
	v_add_f32_e32 v214, v214, v89
	v_cvt_pk_bf16_f32 v75, v86, v87
	v_exp_f32_e32 v93, v93
	v_add_f32_e32 v202, v202, v90
	v_exp_f32_e32 v94, v94
	v_add_f32_e32 v214, v214, v91
	v_cvt_pk_bf16_f32 v76, v88, v89
	v_exp_f32_e32 v95, v95
	v_add_f32_e32 v202, v202, v92
	v_add_f32_e32 v214, v214, v93
	v_cvt_pk_bf16_f32 v77, v90, v91
	v_add_f32_e32 v202, v202, v94
	v_add_f32_e32 v214, v214, v95
	v_cvt_pk_bf16_f32 v78, v92, v93
	v_cvt_pk_bf16_f32 v79, v94, v95
	v_add_f32_e32 v202, v202, v214
	ds_read_b128 v[80:83], v218 offset:13376
	ds_read_b128 v[84:87], v218 offset:17984
	ds_read_b128 v[88:91], v218 offset:13408
	ds_read_b128 v[92:95], v218 offset:18016
	v_exp_f32_e32 v96, v96
	v_exp_f32_e32 v97, v97
	v_exp_f32_e32 v98, v98
	v_exp_f32_e32 v99, v99
	v_add_f32_e32 v203, v203, v96
	v_exp_f32_e32 v100, v100
	v_exp_f32_e32 v101, v101
	v_add_f32_e32 v203, v203, v98
	s_waitcnt lgkmcnt(3)
	v_mfma_f32_32x32x16_bf16 v[16:31], v[80:83], v[72:75], v[16:31]
	v_exp_f32_e32 v102, v102
	v_add_f32_e32 v216, v97, v99
	v_cvt_pk_bf16_f32 v96, v96, v97
	v_exp_f32_e32 v103, v103
	v_add_f32_e32 v203, v203, v100
	v_exp_f32_e32 v104, v104
	v_add_f32_e32 v216, v216, v101
	v_cvt_pk_bf16_f32 v97, v98, v99
	v_exp_f32_e32 v105, v105
	s_waitcnt lgkmcnt(2)
	v_mfma_f32_32x32x16_bf16 v[0:15], v[84:87], v[72:75], v[0:15]
	v_add_f32_e32 v203, v203, v102
	v_exp_f32_e32 v106, v106
	v_add_f32_e32 v216, v216, v103
	v_cvt_pk_bf16_f32 v98, v100, v101
	v_exp_f32_e32 v107, v107
	v_add_f32_e32 v203, v203, v104
	v_exp_f32_e32 v108, v108
	v_add_f32_e32 v216, v216, v105
	v_cvt_pk_bf16_f32 v99, v102, v103
	s_waitcnt lgkmcnt(1)
	v_mfma_f32_32x32x16_bf16 v[16:31], v[88:91], v[76:79], v[16:31]
	v_exp_f32_e32 v109, v109
	v_add_f32_e32 v203, v203, v106
	v_exp_f32_e32 v110, v110
	v_add_f32_e32 v216, v216, v107
	v_cvt_pk_bf16_f32 v100, v104, v105
	v_exp_f32_e32 v111, v111
	v_add_f32_e32 v203, v203, v108
	v_exp_f32_e32 v112, v112
	v_add_f32_e32 v216, v216, v109
	s_waitcnt lgkmcnt(0)
	v_mfma_f32_32x32x16_bf16 v[0:15], v[92:95], v[76:79], v[0:15]
	v_cvt_pk_bf16_f32 v101, v106, v107
	v_exp_f32_e32 v113, v113
	v_add_f32_e32 v203, v203, v110
	v_exp_f32_e32 v114, v114
	v_add_f32_e32 v216, v216, v111
	v_cvt_pk_bf16_f32 v102, v108, v109
	v_exp_f32_e32 v115, v115
	v_add_f32_e32 v203, v203, v112
	v_exp_f32_e32 v116, v116
	v_mfma_f32_32x32x16_bf16 v[48:63], v[236:239], v[96:99], v[48:63]
	v_add_f32_e32 v216, v216, v113
	v_cvt_pk_bf16_f32 v103, v110, v111
	v_exp_f32_e32 v117, v117
	v_add_f32_e32 v203, v203, v114
	v_exp_f32_e32 v118, v118
	v_add_f32_e32 v216, v216, v115
	v_cvt_pk_bf16_f32 v104, v112, v113
	v_exp_f32_e32 v119, v119
	v_add_f32_e32 v203, v203, v116
	v_mfma_f32_32x32x16_bf16 v[32:47], v[240:243], v[96:99], v[32:47]
	v_exp_f32_e32 v120, v120
	v_add_f32_e32 v216, v216, v117
	v_cvt_pk_bf16_f32 v105, v114, v115
	v_exp_f32_e32 v121, v121
	v_add_f32_e32 v203, v203, v118
	v_exp_f32_e32 v122, v122
	v_add_f32_e32 v216, v216, v119
	v_cvt_pk_bf16_f32 v106, v116, v117
	v_exp_f32_e32 v123, v123
	v_mfma_f32_32x32x16_bf16 v[48:63], v[244:247], v[100:103], v[48:63]
	v_add_f32_e32 v203, v203, v120
	v_exp_f32_e32 v124, v124
	v_add_f32_e32 v216, v216, v121
	v_cvt_pk_bf16_f32 v107, v118, v119
	v_exp_f32_e32 v125, v125
	v_add_f32_e32 v203, v203, v122
	v_exp_f32_e32 v126, v126
	v_add_f32_e32 v216, v216, v123
	v_cvt_pk_bf16_f32 v108, v120, v121
	v_mfma_f32_32x32x16_bf16 v[32:47], v[248:251], v[100:103], v[32:47]
	v_exp_f32_e32 v127, v127
	v_add_f32_e32 v203, v203, v124
	v_add_f32_e32 v216, v216, v125
	v_cvt_pk_bf16_f32 v109, v122, v123
	v_add_f32_e32 v203, v203, v126
	v_add_f32_e32 v216, v216, v127
	v_cvt_pk_bf16_f32 v110, v124, v125
	v_cvt_pk_bf16_f32 v111, v126, v127
	v_add_f32_e32 v203, v203, v216
	s_nop 0
	v_mfma_f32_32x32x16_bf16 v[48:63], v[80:83], v[104:107], v[48:63]
	v_mfma_f32_32x32x16_bf16 v[32:47], v[84:87], v[104:107], v[32:47]
	s_cmp_eq_u32 s1, 64
	s_cbranch_scc1 .Lat_nowr
	s_cmp_eq_u32 s4, 1
	s_cselect_b32 s4, 0x5800, 0
	v_add3_u32 v214, s4, v225, v226
	v_add3_u32 v215, s4, v227, v228
	v_add3_u32 v216, s4, v229, v230
	v_add3_u32 v217, s4, v231, v200
	v_add3_u32 v196, s4, v232, v200
	s_waitcnt vmcnt(4)
	ds_write_b128 v214, v[176:179]
	s_waitcnt vmcnt(3)
	ds_write_b128 v215, v[180:183]
	s_waitcnt vmcnt(2)
	ds_write_b128 v216, v[184:187]
	s_waitcnt vmcnt(1)
	ds_write_b128 v217, v[188:191] offset:13312
	s_waitcnt vmcnt(0)
	ds_write_b128 v196, v[192:195] offset:13312
